# attention: nt cache policy on single-use Q / gate loads and mix stores (on top of the GEMM1 nt variant)
# baseline (speedup 1.0000x reference)
.LBB0_444:
	s_or_b64 exec, exec, s[12:13]
	s_lshr_b32 s2, s2, 6
	s_add_u32 s3, s80, 0x14000000
	s_addc_u32 s30, s81, 0
	s_ashr_i32 s11, s10, 31
	s_add_i32 s12, s2, s17
	s_lshl_b64 s[10:11], s[10:11], 12
	s_lshl_b32 s12, s12, 6
	s_add_u32 s10, s10, s12
	s_addc_u32 s11, s11, 0
	s_or_b32 s10, s10, s15
	s_lshl_b64 s[10:11], s[10:11], 10
	s_add_u32 s10, s3, s10
	s_addc_u32 s11, s30, s11
	s_lshl_b32 s13, s16, 7
	s_add_u32 s10, s10, s13
	s_addc_u32 s11, s11, 0
	v_and_b32_e32 v173, 15, v0
	v_mov_b32_e32 v127, 0
	s_add_u32 s8, s8, s12
	v_bfe_u32 v91, v0, 4, 2
	v_lshlrev_b32_e32 v70, 10, v173
	v_mov_b32_e32 v71, v127
	s_addc_u32 s9, s9, 0
	s_or_b32 s8, s8, s15
	v_lshl_add_u64 v[72:73], s[10:11], 0, v[70:71]
	v_lshlrev_b32_e32 v142, 3, v91
	v_mov_b32_e32 v143, v127
	s_lshl_b64 s[8:9], s[8:9], 7
	v_lshl_add_u64 v[72:73], v[72:73], 0, v[142:143]
	s_add_u32 s8, s24, s8
	global_load_dwordx2 v[146:147], v[72:73], off offset:96 nt
	global_load_dwordx2 v[158:159], v[72:73], off offset:64 nt
	global_load_dwordx2 v[160:161], v[72:73], off offset:32 nt
	global_load_dwordx2 v[162:163], v[72:73], off nt
	s_addc_u32 s9, s25, s9
	v_lshlrev_b32_e32 v72, 7, v173
	v_mov_b32_e32 v73, v127
	v_lshl_add_u64 v[74:75], s[8:9], 0, v[72:73]
	v_lshlrev_b32_e32 v88, 4, v91
	v_mov_b32_e32 v89, v127
	v_lshl_add_u64 v[78:79], v[74:75], 0, v[88:89]
	global_load_dwordx4 v[74:77], v[78:79], off offset:64 nt
	s_nop 0
	global_load_dwordx4 v[78:81], v[78:79], off nt
	v_lshrrev_b32_e32 v96, 5, v0
	v_and_b32_e32 v94, 7, v0
	v_bfe_u32 v95, v0, 4, 1
	v_and_b32_e32 v96, 6, v96
	v_bitop3_b32 v94, v95, v94, v96 bitop3:0x36
	v_and_b32_e32 v67, 0xf80, v69
	v_lshlrev_b32_e32 v94, 4, v94
	v_add3_u32 v143, 0, v67, v94
	v_bitop3_b32 v67, v69, 48, v0 bitop3:0x48
	v_add3_u32 v174, 0, v85, v67
	v_mov_b32_e32 v67, v127
	v_lshl_add_u64 v[66:67], s[0:1], 0, v[66:67]
	v_mov_b32_e32 v69, v127
	v_lshl_add_u64 v[148:149], v[66:67], 0, v[68:69]
	v_lshl_add_u64 v[66:67], s[24:25], 0, v[72:73]
	v_lshrrev_b32_e32 v71, 4, v0
	v_lshl_add_u64 v[150:151], v[66:67], 0, v[88:89]
	v_bfe_u32 v66, v0, 1, 3
	v_bitop3_b32 v67, v71, v66, 3 bitop3:0x6c
	v_bitop3_b32 v66, v91, v66, 4 bitop3:0x36
	v_lshlrev_b32_e32 v178, 4, v66
	v_mbcnt_lo_u32_b32 v66, -1, 0
	v_mbcnt_hi_u32_b32 v66, -1, v66
	v_and_b32_e32 v68, 64, v66
	v_lshlrev_b32_e32 v177, 4, v67
	v_xor_b32_e32 v67, 16, v66
	v_add_u32_e32 v68, 64, v68
	v_cmp_lt_i32_e32 vcc, v67, v68
	v_lshlrev_b32_e32 v93, 6, v173
	v_lshlrev_b32_e32 v92, 1, v0
	v_cndmask_b32_e32 v67, v66, v67, vcc
	v_lshlrev_b32_e32 v179, 2, v67
	v_xor_b32_e32 v67, 32, v66
	v_cmp_lt_i32_e32 vcc, v67, v68
	v_lshlrev_b32_e32 v90, 9, v173
	s_movk_i32 s8, 0x1d1
	v_cndmask_b32_e32 v66, v66, v67, vcc
	v_lshlrev_b32_e32 v180, 2, v66
	v_xor_b32_e32 v66, v71, v82
	v_lshlrev_b32_e32 v66, 4, v66
	v_and_b32_e32 v66, 48, v66
	v_add3_u32 v181, 0, v93, v66
	v_lshlrev_b32_e32 v66, 4, v87
	s_add_i32 s10, 0, 0x1e100
	v_and_b32_e32 v152, 0xf000, v66
	v_and_or_b32 v66, v92, 24, v83
	v_lshlrev_b32_e32 v144, 2, v91
	v_add_u32_e32 v175, 0xf000, v174
	v_cmp_gt_u32_e64 s[8:9], s8, v0
	v_lshl_add_u32 v176, v0, 2, s10
	v_lshl_add_u32 v182, v66, 7, 0
	s_lshl_b32 s31, s82, 1
	v_add_u32_e32 v183, v174, v84
	v_add_u32_e32 v184, v174, v86
	v_lshlrev_b32_e32 v154, 1, v90
	s_mov_b32 s33, 0xff800000
	v_lshlrev_b32_e32 v156, 1, v70
	v_mov_b32_e32 v185, 0x358637bd
	s_mov_b32 s34, 0x800000
	v_mov_b32_e32 v186, 0xff800000
	s_mov_b32 s48, -1
	s_mov_b32 s15, s86
	s_branch .LBB0_447
.LBB0_445:
	s_or_b64 exec, exec, s[12:13]
	s_add_i32 s1, s1, s2
	s_lshl_b32 s12, s1, 6
	s_add_u32 s1, s10, s12
	s_addc_u32 s11, s11, 0
	s_or_b32 s10, s1, s19
	s_ashr_i32 s1, s0, 31
	s_lshl_b64 s[10:11], s[10:11], 7
	s_lshl_b64 s[0:1], s[0:1], 12
	s_add_u32 s0, s0, s12
	s_addc_u32 s1, s1, 0
	s_or_b32 s0, s0, s19
	s_lshl_b64 s[0:1], s[0:1], 10
	s_add_u32 s0, s3, s0
	v_lshl_add_u64 v[70:71], v[150:151], 0, s[10:11]
	s_addc_u32 s1, s30, s1
	s_lshl_b32 s10, s18, 7
	s_add_u32 s0, s0, s10
	s_addc_u32 s1, s1, 0
	v_mov_b32_e32 v155, v127
	v_lshl_add_u64 v[66:67], s[0:1], 0, v[154:155]
	v_lshlrev_b32_e32 v68, 1, v144
	v_mov_b32_e32 v69, v127
	v_lshl_add_u64 v[82:83], v[66:67], 0, v[68:69]
	global_load_dwordx4 v[66:69], v[70:71], off nt
	s_nop 0
	global_load_dwordx4 v[70:73], v[70:71], off offset:64 nt
	s_nop 0
	global_load_dwordx2 v[164:165], v[82:83], off nt
	global_load_dwordx2 v[166:167], v[82:83], off offset:32 nt
	global_load_dwordx2 v[168:169], v[82:83], off offset:64 nt
	global_load_dwordx2 v[170:171], v[82:83], off offset:96 nt
.LBB0_446:
	s_add_i32 s16, s16, s2
	s_max_i32 s11, s16, 4
	s_ashr_i32 s10, s15, 8
	s_add_i32 s11, s11, -4
	s_min_u32 s1, s17, 49
	s_min_u32 s12, s11, 56
	s_ashr_i32 s11, s10, 31
	s_and_b32 s0, s14, 48
	s_sub_i32 s13, s12, s1
	s_lshl_b64 s[10:11], s[10:11], 12
	s_lshl_b32 s1, s16, 6
	s_add_u32 s10, s10, s1
	s_addc_u32 s1, s11, 0
	s_lshl_b32 s46, s13, 12
	v_add_u32_e32 v83, s46, v182
	v_add_u32_e32 v129, v83, v177
	v_add_u32_e32 v131, v83, v178
	ds_read_b128 v[84:87], v129
	ds_read_b128 v[88:91], v129 offset:512
	ds_read_b128 v[92:95], v131
	ds_read_b128 v[96:99], v131 offset:512
	s_waitcnt vmcnt(18) lgkmcnt(3)
	v_mfma_f32_16x16x32_bf16 v[84:87], v[84:87], v[78:81], 0
	v_sub_u32_e64 v82, s0, 8 clamp
	v_min_u32_e32 v133, 32, v82
	v_or_b32_e32 v135, s0, v173
	s_waitcnt lgkmcnt(2)
	v_mfma_f32_16x16x32_bf16 v[88:91], v[88:91], v[78:81], 0
	s_or_b32 s0, s10, s0
	s_lshl_b64 s[0:1], s[0:1], 11
	s_add_i32 s47, s46, 0x1000
	s_waitcnt lgkmcnt(1)
	v_mfma_f32_16x16x32_bf16 v[188:191], v[92:95], v[74:77], v[84:87]
	s_add_i32 s45, s46, 0x2000
	s_add_i32 s44, s46, 0x3000
	s_add_i32 s43, s46, 0x4000
	s_waitcnt lgkmcnt(0)
	v_mfma_f32_16x16x32_bf16 v[192:195], v[96:99], v[74:77], v[88:91]
	ds_read_b128 v[84:87], v129 offset:4096
	s_nop 1
	ds_read_b128 v[88:91], v129 offset:4608
	ds_read_b128 v[92:95], v131 offset:4096
	ds_read_b128 v[96:99], v131 offset:4608
	s_add_i32 s42, s46, 0x5000
	s_waitcnt lgkmcnt(3)
	v_mfma_f32_16x16x32_bf16 v[84:87], v[84:87], v[78:81], 0
	s_add_i32 s41, s46, 0x6000
	s_add_i32 s40, s46, 0x7000
	s_add_u32 s38, s80, s0
	s_waitcnt lgkmcnt(1)
	v_mfma_f32_16x16x32_bf16 v[196:199], v[92:95], v[74:77], v[84:87]
	s_addc_u32 s39, s81, s1
	s_sub_i32 s0, s12, s16
	s_mulk_i32 s0, 0x7c
	v_mfma_f32_16x16x32_bf16 v[84:87], v[88:91], v[78:81], 0
	s_add_i32 s0, s0, 0
	s_add_i32 s0, s0, 0x1e100
	s_waitcnt lgkmcnt(0)
	v_mfma_f32_16x16x32_bf16 v[200:203], v[96:99], v[74:77], v[84:87]
	s_nop 3
	ds_read_b128 v[84:87], v129 offset:8192
	ds_read_b128 v[88:91], v129 offset:8704
	ds_read_b128 v[92:95], v131 offset:8192
	ds_read_b128 v[96:99], v131 offset:8704
	s_waitcnt lgkmcnt(3)
	v_mfma_f32_16x16x32_bf16 v[84:87], v[84:87], v[78:81], 0
	s_waitcnt lgkmcnt(1)
	v_mfma_f32_16x16x32_bf16 v[122:125], v[92:95], v[74:77], v[84:87]
	ds_read_b128 v[92:95], v131 offset:12288
	v_mfma_f32_16x16x32_bf16 v[84:87], v[88:91], v[78:81], 0
	ds_read_b128 v[88:91], v129 offset:12288
	s_waitcnt lgkmcnt(2)
	v_mfma_f32_16x16x32_bf16 v[118:121], v[96:99], v[74:77], v[84:87]
	v_max_i32_e32 v96, 8, v135
	v_add_u32_e32 v137, -8, v96
	ds_read_b128 v[96:99], v131 offset:12800
	s_nop 1
	ds_read_b128 v[82:85], v129 offset:12800
	s_waitcnt lgkmcnt(2)
	v_mfma_f32_16x16x32_bf16 v[86:89], v[88:91], v[78:81], 0
	v_mfma_f32_16x16x32_bf16 v[110:113], v[92:95], v[74:77], v[86:89]
	ds_read_b128 v[90:93], v131 offset:16384
	s_nop 5
	ds_read_b128 v[86:89], v129 offset:16384
	s_waitcnt lgkmcnt(2)
	v_mfma_f32_16x16x32_bf16 v[82:85], v[82:85], v[78:81], 0
	v_mfma_f32_16x16x32_bf16 v[114:117], v[96:99], v[74:77], v[82:85]
	s_nop 6
	ds_read_b128 v[82:85], v129 offset:16896
	ds_read_b128 v[94:97], v131 offset:16896
	ds_read_b128 v[98:101], v129 offset:20480
	ds_read_b128 v[204:207], v129 offset:20992
	s_waitcnt lgkmcnt(4)
	v_mfma_f32_16x16x32_bf16 v[86:89], v[86:89], v[78:81], 0
	s_waitcnt lgkmcnt(3)
	v_mfma_f32_16x16x32_bf16 v[82:85], v[82:85], v[78:81], 0
	v_mfma_f32_16x16x32_bf16 v[102:105], v[90:93], v[74:77], v[86:89]
	s_nop 4
	ds_read_b128 v[86:89], v131 offset:20480
	ds_read_b128 v[90:93], v131 offset:20992
	ds_read_b128 v[208:211], v129 offset:24576
	ds_read_b128 v[212:215], v129 offset:25088
	ds_read_b128 v[216:219], v131 offset:24576
	ds_read_b128 v[220:223], v131 offset:25088
	ds_read_b128 v[224:227], v129 offset:28672
	ds_read_b128 v[228:231], v129 offset:29184
	s_waitcnt lgkmcnt(10)
	v_mfma_f32_16x16x32_bf16 v[106:109], v[94:97], v[74:77], v[82:85]
	ds_read_b128 v[232:235], v131 offset:28672
	ds_read_b128 v[236:239], v131 offset:29184
	v_add_u32_e32 v131, v133, v142
	v_min_u32_e32 v129, 48, v137
	s_waitcnt lgkmcnt(11)
	v_mfma_f32_16x16x32_bf16 v[82:85], v[98:101], v[78:81], 0
	v_cmp_ge_u32_e32 vcc, v131, v129
	v_or_b32_e32 v139, 1, v131
	v_or_b32_e32 v155, 2, v131
	s_waitcnt lgkmcnt(9)
	v_mfma_f32_16x16x32_bf16 v[94:97], v[86:89], v[74:77], v[82:85]
	v_or_b32_e32 v157, 3, v131
	v_mfma_f32_16x16x32_bf16 v[82:85], v[204:207], v[78:81], 0
	s_waitcnt lgkmcnt(8)
	v_mfma_f32_16x16x32_bf16 v[90:93], v[90:93], v[74:77], v[82:85]
	s_waitcnt lgkmcnt(6)
	v_mfma_f32_16x16x32_bf16 v[86:89], v[212:215], v[78:81], 0
	s_nop 3
	v_sub_u32_e32 v82, v131, v135
	v_lshl_add_u32 v133, v82, 2, s0
	ds_read2_b32 v[204:205], v133 offset0:232 offset1:233
	v_add_u32_e32 v135, 16, v129
	v_cmp_lt_u32_e64 s[0:1], v131, v135
	s_and_b64 vcc, vcc, s[0:1]
	v_mfma_f32_16x16x32_bf16 v[82:85], v[208:211], v[78:81], 0
	s_waitcnt lgkmcnt(0)
	v_add_f32_e32 v98, v188, v204
	v_cndmask_b32_e32 v137, v186, v98, vcc
	ds_read2_b32 v[206:207], v133 offset0:234 offset1:235
	ds_read2_b32 v[208:209], v133 offset0:236 offset1:237
	ds_read2_b32 v[210:211], v133 offset0:238 offset1:239
	v_mfma_f32_16x16x32_bf16 v[98:101], v[220:223], v[74:77], v[86:89]
	v_cmp_ge_u32_e64 s[0:1], v139, v129
	v_cmp_lt_u32_e64 s[10:11], v139, v135
	s_and_b64 s[10:11], s[0:1], s[10:11]
	v_mfma_f32_16x16x32_bf16 v[86:89], v[224:227], v[78:81], 0
	v_cmp_ge_u32_e64 s[0:1], v155, v129
	v_cmp_lt_u32_e64 s[12:13], v155, v135
	v_add_f32_e32 v139, v189, v205
	v_mfma_f32_16x16x32_bf16 v[78:81], v[228:231], v[78:81], 0
	s_and_b64 s[12:13], s[0:1], s[12:13]
	v_cmp_ge_u32_e64 s[0:1], v157, v129
	v_cmp_lt_u32_e64 s[14:15], v157, v135
	v_mfma_f32_16x16x32_bf16 v[82:85], v[216:219], v[74:77], v[82:85]
	v_cndmask_b32_e64 v139, v186, v139, s[10:11]
	s_waitcnt lgkmcnt(2)
	v_add_f32_e32 v155, v190, v206
	s_and_b64 s[14:15], s[0:1], s[14:15]
	v_mfma_f32_16x16x32_bf16 v[86:89], v[232:235], v[74:77], v[86:89]
	v_max3_f32 v141, v137, s33, v139
	v_cndmask_b32_e64 v155, v186, v155, s[12:13]
	v_add_u32_e32 v190, 0x434, v133
	v_mfma_f32_16x16x32_bf16 v[74:77], v[236:239], v[74:77], v[78:81]
	s_nop 2
	v_or_b32_e32 v79, 4, v131
	v_add_f32_e32 v78, v191, v207
	v_cmp_ge_u32_e64 s[0:1], v79, v129
	v_cmp_lt_u32_e64 s[16:17], v79, v135
	v_cndmask_b32_e64 v157, v186, v78, s[14:15]
	s_waitcnt lgkmcnt(1)
	v_add_f32_e32 v79, v192, v208
	s_and_b64 s[16:17], s[0:1], s[16:17]
	v_max3_f32 v78, v141, v155, v157
	v_cndmask_b32_e64 v141, v186, v79, s[16:17]
	v_or_b32_e32 v79, 5, v131
	v_cmp_ge_u32_e64 s[0:1], v79, v129
	v_cmp_lt_u32_e64 s[18:19], v79, v135
	v_add_f32_e32 v79, v193, v209
	s_and_b64 s[18:19], s[0:1], s[18:19]
	v_cndmask_b32_e64 v187, v186, v79, s[18:19]
	v_or_b32_e32 v79, 6, v131
	v_cmp_ge_u32_e64 s[0:1], v79, v129
	v_cmp_lt_u32_e64 s[20:21], v79, v135
	s_waitcnt lgkmcnt(0)
	v_add_f32_e32 v79, v194, v210
	s_and_b64 s[20:21], s[0:1], s[20:21]
	v_cndmask_b32_e64 v192, v186, v79, s[20:21]
	v_or_b32_e32 v79, 7, v131
	v_cmp_ge_u32_e64 s[0:1], v79, v129
	v_cmp_lt_u32_e64 s[22:23], v79, v135
	v_add_f32_e32 v79, v195, v211
	s_and_b64 s[22:23], s[0:1], s[22:23]
	v_max3_f32 v78, v78, v141, v187
	v_cndmask_b32_e64 v129, v186, v79, s[22:23]
	v_max3_f32 v131, v78, v192, v129
	v_add_u32_e32 v78, 0x41c, v133
	ds_read2_b32 v[78:79], v78 offset1:1
	v_add_u32_e32 v80, 0x424, v133
	v_add_u32_e32 v135, 0x42c, v133
	ds_read2_b32 v[80:81], v80 offset1:1
	ds_read2_b32 v[188:189], v135 offset1:1
	ds_read2_b32 v[190:191], v190 offset1:1
	s_lshl_b32 s0, s37, 7
	s_waitcnt lgkmcnt(3)
	v_add_f32_e32 v78, v196, v78
	v_cndmask_b32_e32 v135, v186, v78, vcc
	v_add_f32_e32 v78, v197, v79
	v_cndmask_b32_e64 v193, v186, v78, s[10:11]
	s_waitcnt lgkmcnt(2)
	v_add_f32_e32 v79, v198, v80
	v_max3_f32 v78, v131, v135, v193
	v_cndmask_b32_e64 v131, v186, v79, s[12:13]
	v_add_f32_e32 v79, v199, v81
	v_cndmask_b32_e64 v194, v186, v79, s[14:15]
	s_waitcnt lgkmcnt(1)
	v_add_f32_e32 v79, v200, v188
	v_cndmask_b32_e64 v195, v186, v79, s[16:17]
	v_add_f32_e32 v79, v201, v189
	v_cndmask_b32_e64 v196, v186, v79, s[18:19]
	s_waitcnt lgkmcnt(0)
	v_add_f32_e32 v79, v202, v190
	v_max3_f32 v78, v78, v131, v194
	v_cndmask_b32_e64 v197, v186, v79, s[20:21]
	v_add_f32_e32 v79, v203, v191
	v_max3_f32 v78, v78, v195, v196
	v_cndmask_b32_e64 v198, v186, v79, s[22:23]
	v_max3_f32 v199, v78, v197, v198
	v_add_u32_e32 v78, 0x498, v133
	ds_read2_b32 v[78:79], v78 offset1:1
	v_add_u32_e32 v80, 0x4a0, v133
	v_add_u32_e32 v188, 0x4a8, v133
	v_add_u32_e32 v190, 0x4b0, v133
	ds_read2_b32 v[80:81], v80 offset1:1
	ds_read2_b32 v[188:189], v188 offset1:1
	ds_read2_b32 v[190:191], v190 offset1:1
	s_waitcnt lgkmcnt(3)
	v_add_f32_e32 v78, v122, v78
	v_cndmask_b32_e32 v122, v186, v78, vcc
	v_add_f32_e32 v78, v123, v79
	s_waitcnt lgkmcnt(2)
	v_add_f32_e32 v79, v124, v80
	v_cndmask_b32_e64 v124, v186, v79, s[12:13]
	v_add_f32_e32 v79, v125, v81
	v_cndmask_b32_e64 v125, v186, v79, s[14:15]
	s_waitcnt lgkmcnt(1)
	v_add_f32_e32 v79, v118, v188
	v_cndmask_b32_e64 v123, v186, v78, s[10:11]
	v_cndmask_b32_e64 v188, v186, v79, s[16:17]
	v_add_f32_e32 v79, v119, v189
	v_max3_f32 v78, v199, v122, v123
	v_cndmask_b32_e64 v189, v186, v79, s[18:19]
	s_waitcnt lgkmcnt(0)
	v_add_f32_e32 v79, v120, v190
	v_max3_f32 v78, v78, v124, v125
	v_cndmask_b32_e64 v190, v186, v79, s[20:21]
	v_add_f32_e32 v79, v121, v191
	v_max3_f32 v78, v78, v188, v189
	v_cndmask_b32_e64 v191, v186, v79, s[22:23]
	v_max3_f32 v199, v78, v190, v191
	v_add_u32_e32 v78, 0x514, v133
	ds_read2_b32 v[78:79], v78 offset1:1
	v_add_u32_e32 v80, 0x51c, v133
	v_add_u32_e32 v118, 0x524, v133
	v_add_u32_e32 v120, 0x52c, v133
	ds_read2_b32 v[80:81], v80 offset1:1
	ds_read2_b32 v[118:119], v118 offset1:1
	ds_read2_b32 v[120:121], v120 offset1:1
	s_waitcnt lgkmcnt(3)
	v_add_f32_e32 v78, v110, v78
	v_cndmask_b32_e32 v200, v186, v78, vcc
	v_add_f32_e32 v78, v111, v79
	v_cndmask_b32_e64 v201, v186, v78, s[10:11]
	s_waitcnt lgkmcnt(2)
	v_add_f32_e32 v79, v112, v80
	v_max3_f32 v78, v199, v200, v201
	v_cndmask_b32_e64 v199, v186, v79, s[12:13]
	v_add_f32_e32 v79, v113, v81
	v_cndmask_b32_e64 v202, v186, v79, s[14:15]
	s_waitcnt lgkmcnt(1)
	v_add_f32_e32 v79, v114, v118
	v_cndmask_b32_e64 v114, v186, v79, s[16:17]
	v_add_f32_e32 v79, v115, v119
	v_cndmask_b32_e64 v115, v186, v79, s[18:19]
	s_waitcnt lgkmcnt(0)
	v_add_f32_e32 v79, v116, v120
	v_max3_f32 v78, v78, v199, v202
	v_cndmask_b32_e64 v116, v186, v79, s[20:21]
	v_add_f32_e32 v79, v117, v121
	v_max3_f32 v78, v78, v114, v115
	v_cndmask_b32_e64 v117, v186, v79, s[22:23]
	v_max3_f32 v118, v78, v116, v117
	v_add_u32_e32 v78, 0x590, v133
	ds_read2_b32 v[78:79], v78 offset1:1
	v_add_u32_e32 v80, 0x598, v133
	v_add_u32_e32 v110, 0x5a0, v133
	v_add_u32_e32 v112, 0x5a8, v133
	ds_read2_b32 v[80:81], v80 offset1:1
	ds_read2_b32 v[110:111], v110 offset1:1
	ds_read2_b32 v[112:113], v112 offset1:1
	s_waitcnt lgkmcnt(3)
	v_add_f32_e32 v78, v102, v78
	v_cndmask_b32_e32 v119, v186, v78, vcc
	v_add_f32_e32 v78, v103, v79
	v_cndmask_b32_e64 v120, v186, v78, s[10:11]
	s_waitcnt lgkmcnt(2)
	v_add_f32_e32 v79, v104, v80
	v_max3_f32 v78, v118, v119, v120
	v_cndmask_b32_e64 v118, v186, v79, s[12:13]
	v_add_f32_e32 v79, v105, v81
	v_cndmask_b32_e64 v121, v186, v79, s[14:15]
	s_waitcnt lgkmcnt(1)
	v_add_f32_e32 v79, v106, v110
	v_cndmask_b32_e64 v106, v186, v79, s[16:17]
	v_add_f32_e32 v79, v107, v111
	v_cndmask_b32_e64 v107, v186, v79, s[18:19]
	s_waitcnt lgkmcnt(0)
	v_add_f32_e32 v79, v108, v112
	v_max3_f32 v78, v78, v118, v121
	v_cndmask_b32_e64 v108, v186, v79, s[20:21]
	v_add_f32_e32 v79, v109, v113
	v_max3_f32 v78, v78, v106, v107
	v_cndmask_b32_e64 v109, v186, v79, s[22:23]
	v_max3_f32 v110, v78, v108, v109
	v_add_u32_e32 v78, 0x60c, v133
	ds_read2_b32 v[78:79], v78 offset1:1
	v_add_u32_e32 v80, 0x614, v133
	v_add_u32_e32 v102, 0x61c, v133
	v_add_u32_e32 v104, 0x624, v133
	ds_read2_b32 v[80:81], v80 offset1:1
	ds_read2_b32 v[102:103], v102 offset1:1
	ds_read2_b32 v[104:105], v104 offset1:1
	s_waitcnt lgkmcnt(3)
	v_add_f32_e32 v78, v94, v78
	v_cndmask_b32_e32 v94, v186, v78, vcc
	v_add_f32_e32 v78, v95, v79
	s_waitcnt lgkmcnt(2)
	v_add_f32_e32 v79, v96, v80
	v_cndmask_b32_e64 v96, v186, v79, s[12:13]
	v_add_f32_e32 v79, v97, v81
	v_cndmask_b32_e64 v97, v186, v79, s[14:15]
	s_waitcnt lgkmcnt(1)
	v_add_f32_e32 v79, v90, v102
	v_cndmask_b32_e64 v95, v186, v78, s[10:11]
	v_cndmask_b32_e64 v102, v186, v79, s[16:17]
	v_add_f32_e32 v79, v91, v103
	v_max3_f32 v78, v110, v94, v95
	v_cndmask_b32_e64 v103, v186, v79, s[18:19]
	s_waitcnt lgkmcnt(0)
	v_add_f32_e32 v79, v92, v104
	v_max3_f32 v78, v78, v96, v97
	v_cndmask_b32_e64 v104, v186, v79, s[20:21]
	v_add_f32_e32 v79, v93, v105
	v_max3_f32 v78, v78, v102, v103
	v_cndmask_b32_e64 v105, v186, v79, s[22:23]
	v_max3_f32 v110, v78, v104, v105
	v_add_u32_e32 v78, 0x688, v133
	ds_read2_b32 v[78:79], v78 offset1:1
	v_add_u32_e32 v80, 0x690, v133
	v_add_u32_e32 v90, 0x698, v133
	v_add_u32_e32 v92, 0x6a0, v133
	ds_read2_b32 v[80:81], v80 offset1:1
	ds_read2_b32 v[90:91], v90 offset1:1
	ds_read2_b32 v[92:93], v92 offset1:1
	s_waitcnt lgkmcnt(3)
	v_add_f32_e32 v78, v82, v78
	v_cndmask_b32_e32 v111, v186, v78, vcc
	v_add_f32_e32 v78, v83, v79
	v_cndmask_b32_e64 v112, v186, v78, s[10:11]
	s_waitcnt lgkmcnt(2)
	v_add_f32_e32 v79, v84, v80
	v_max3_f32 v78, v110, v111, v112
	v_cndmask_b32_e64 v110, v186, v79, s[12:13]
	v_add_f32_e32 v79, v85, v81
	v_cndmask_b32_e64 v113, v186, v79, s[14:15]
	s_waitcnt lgkmcnt(1)
	v_add_f32_e32 v79, v98, v90
	v_cndmask_b32_e64 v203, v186, v79, s[16:17]
	v_add_f32_e32 v79, v99, v91
	v_cndmask_b32_e64 v204, v186, v79, s[18:19]
	s_waitcnt lgkmcnt(0)
	v_add_f32_e32 v79, v100, v92
	v_max3_f32 v78, v78, v110, v113
	v_cndmask_b32_e64 v205, v186, v79, s[20:21]
	v_add_f32_e32 v79, v101, v93
	v_max3_f32 v78, v78, v203, v204
	v_cndmask_b32_e64 v206, v186, v79, s[22:23]
	v_max3_f32 v90, v78, v205, v206
	v_add_u32_e32 v78, 0x704, v133
	ds_read2_b32 v[78:79], v78 offset1:1
	v_add_u32_e32 v80, 0x70c, v133
	v_add_u32_e32 v82, 0x714, v133
	v_add_u32_e32 v84, 0x71c, v133
	ds_read2_b32 v[80:81], v80 offset1:1
	ds_read2_b32 v[82:83], v82 offset1:1
	ds_read2_b32 v[84:85], v84 offset1:1
	s_waitcnt lgkmcnt(3)
	v_add_f32_e32 v78, v86, v78
	v_cndmask_b32_e32 v133, v186, v78, vcc
	v_add_f32_e32 v78, v87, v79
	s_waitcnt lgkmcnt(2)
	v_add_f32_e32 v79, v88, v80
	v_cndmask_b32_e64 v207, v186, v78, s[10:11]
	v_cndmask_b32_e64 v208, v186, v79, s[12:13]
	v_add_f32_e32 v79, v89, v81
	s_waitcnt lgkmcnt(1)
	v_add_f32_e32 v74, v74, v82
	v_max3_f32 v78, v90, v133, v207
	v_cndmask_b32_e64 v209, v186, v79, s[14:15]
	v_cndmask_b32_e64 v210, v186, v74, s[16:17]
	v_add_f32_e32 v74, v75, v83
	s_waitcnt lgkmcnt(0)
	v_add_f32_e32 v75, v76, v84
	v_max3_f32 v78, v78, v208, v209
	v_cndmask_b32_e64 v211, v186, v74, s[18:19]
	v_cndmask_b32_e64 v212, v186, v75, s[20:21]
	v_add_f32_e32 v75, v77, v85
	v_max3_f32 v74, v78, v210, v211
	v_cndmask_b32_e64 v213, v186, v75, s[22:23]
	v_max3_f32 v74, v74, v212, v213
	ds_bpermute_b32 v75, v179, v74
	v_add_u32_e32 v90, s46, v181
	s_add_u32 s0, s38, s0
	s_addc_u32 s1, s39, 0
	s_mov_b32 s14, s36
	s_waitcnt lgkmcnt(0)
	v_max_f32_e32 v75, v75, v75
	v_max_f32_e32 v74, v74, v75
	ds_bpermute_b32 v75, v180, v74
	s_mov_b32 s15, s35
	s_waitcnt lgkmcnt(0)
	v_max_f32_e32 v75, v75, v75
	v_max_f32_e32 v214, v74, v75
	v_sub_f32_e32 v74, v137, v214
	v_exp_f32_e32 v78, v74
	v_sub_f32_e32 v74, v139, v214
	v_exp_f32_e32 v79, v74
	v_sub_f32_e32 v74, v155, v214
	v_exp_f32_e32 v80, v74
	v_sub_f32_e32 v74, v157, v214
	v_exp_f32_e32 v81, v74
	v_sub_f32_e32 v75, v141, v214
	v_add_f32_e32 v74, 0, v78
	v_exp_f32_e32 v86, v75
	v_sub_f32_e32 v75, v187, v214
	v_add_f32_e32 v74, v79, v74
	v_exp_f32_e32 v87, v75
	v_sub_f32_e32 v75, v192, v214
	v_add_f32_e32 v74, v80, v74
	v_exp_f32_e32 v88, v75
	v_sub_f32_e32 v75, v129, v214
	v_add_f32_e32 v74, v81, v74
	v_exp_f32_e32 v89, v75
	v_sub_f32_e32 v75, v135, v214
	v_add_f32_e32 v74, v86, v74
	v_exp_f32_e32 v98, v75
	v_sub_f32_e32 v75, v193, v214
	v_add_f32_e32 v74, v87, v74
	v_exp_f32_e32 v99, v75
	v_sub_f32_e32 v75, v131, v214
	v_add_f32_e32 v74, v88, v74
	v_exp_f32_e32 v129, v75
	v_sub_f32_e32 v75, v194, v214
	v_add_f32_e32 v74, v89, v74
	v_exp_f32_e32 v131, v75
	v_sub_f32_e32 v75, v195, v214
	v_add_f32_e32 v74, v98, v74
	v_exp_f32_e32 v135, v75
	v_sub_f32_e32 v75, v196, v214
	v_add_f32_e32 v74, v99, v74
	v_exp_f32_e32 v137, v75
	v_sub_f32_e32 v75, v197, v214
	v_add_f32_e32 v74, v129, v74
	v_exp_f32_e32 v139, v75
	v_sub_f32_e32 v75, v198, v214
	v_add_f32_e32 v74, v131, v74
	v_exp_f32_e32 v141, v75
	v_sub_f32_e32 v75, v122, v214
	v_add_f32_e32 v74, v135, v74
	v_exp_f32_e32 v122, v75
	v_sub_f32_e32 v75, v123, v214
	v_add_f32_e32 v74, v137, v74
	v_exp_f32_e32 v123, v75
	v_sub_f32_e32 v75, v124, v214
	v_add_f32_e32 v74, v139, v74
	v_exp_f32_e32 v124, v75
	v_sub_f32_e32 v75, v125, v214
	v_add_f32_e32 v74, v141, v74
	v_exp_f32_e32 v125, v75
	v_sub_f32_e32 v75, v188, v214
	v_add_f32_e32 v74, v122, v74
	v_exp_f32_e32 v155, v75
	v_sub_f32_e32 v75, v189, v214
	v_add_f32_e32 v74, v123, v74
	v_exp_f32_e32 v157, v75
	v_sub_f32_e32 v75, v190, v214
	v_add_f32_e32 v74, v124, v74
	v_exp_f32_e32 v187, v75
	v_sub_f32_e32 v75, v191, v214
	v_add_f32_e32 v74, v125, v74
	v_exp_f32_e32 v188, v75
	v_sub_f32_e32 v75, v200, v214
	v_add_f32_e32 v74, v155, v74
	v_exp_f32_e32 v189, v75
	v_sub_f32_e32 v75, v201, v214
	v_add_f32_e32 v74, v157, v74
	v_exp_f32_e32 v190, v75
	v_sub_f32_e32 v75, v199, v214
	v_add_f32_e32 v74, v187, v74
	v_exp_f32_e32 v191, v75
	v_sub_f32_e32 v75, v202, v214
	v_add_f32_e32 v74, v188, v74
	v_exp_f32_e32 v192, v75
	v_sub_f32_e32 v75, v114, v214
	v_add_f32_e32 v74, v189, v74
	v_exp_f32_e32 v114, v75
	v_sub_f32_e32 v75, v115, v214
	v_add_f32_e32 v74, v190, v74
	v_exp_f32_e32 v115, v75
	v_sub_f32_e32 v75, v116, v214
	v_add_f32_e32 v74, v191, v74
	v_exp_f32_e32 v116, v75
	v_sub_f32_e32 v75, v117, v214
	v_add_f32_e32 v74, v192, v74
	v_exp_f32_e32 v117, v75
	v_sub_f32_e32 v75, v119, v214
	v_add_f32_e32 v74, v114, v74
	v_exp_f32_e32 v119, v75
	v_sub_f32_e32 v75, v120, v214
	v_add_f32_e32 v74, v115, v74
	v_exp_f32_e32 v120, v75
	v_sub_f32_e32 v75, v118, v214
	v_add_f32_e32 v74, v116, v74
	v_exp_f32_e32 v118, v75
	v_sub_f32_e32 v75, v121, v214
	v_add_f32_e32 v74, v117, v74
	v_exp_f32_e32 v121, v75
	v_sub_f32_e32 v75, v106, v214
	v_add_f32_e32 v74, v119, v74
	v_exp_f32_e32 v106, v75
	v_sub_f32_e32 v75, v107, v214
	v_add_f32_e32 v74, v120, v74
	v_exp_f32_e32 v107, v75
	v_sub_f32_e32 v75, v108, v214
	v_add_f32_e32 v74, v118, v74
	v_exp_f32_e32 v108, v75
	v_sub_f32_e32 v75, v109, v214
	v_add_f32_e32 v74, v121, v74
	v_exp_f32_e32 v109, v75
	v_sub_f32_e32 v75, v94, v214
	v_add_f32_e32 v74, v106, v74
	v_exp_f32_e32 v193, v75
	v_sub_f32_e32 v75, v95, v214
	v_add_f32_e32 v74, v107, v74
	v_exp_f32_e32 v194, v75
	v_sub_f32_e32 v75, v96, v214
	v_add_f32_e32 v74, v108, v74
	v_exp_f32_e32 v195, v75
	v_sub_f32_e32 v75, v97, v214
	v_add_f32_e32 v74, v109, v74
	v_exp_f32_e32 v196, v75
	v_add_f32_e32 v74, v193, v74
	v_add_f32_e32 v74, v194, v74
	v_add_f32_e32 v74, v195, v74
	v_add_f32_e32 v82, v196, v74
	v_sub_f32_e32 v74, v102, v214
	v_exp_f32_e32 v102, v74
	v_sub_f32_e32 v74, v103, v214
	v_exp_f32_e32 v103, v74
	v_sub_f32_e32 v91, v104, v214
	v_exp_f32_e32 v104, v91
	v_sub_f32_e32 v91, v105, v214
	v_exp_f32_e32 v105, v91
	v_add_f32_e32 v82, v102, v82
	v_add_f32_e32 v94, v103, v82
	v_add_f32_e32 v94, v104, v94
	v_sub_f32_e32 v100, v111, v214
	v_add_u32_e32 v111, s47, v181
	ds_read_b128 v[74:77], v90 offset:61440
	ds_read_b128 v[82:85], v90 offset:62464
	v_cvt_pk_bf16_f32 v78, v78, v79
	v_cvt_pk_bf16_f32 v79, v80, v81
	v_cvt_pk_bf16_f32 v80, v86, v87
	v_cvt_pk_bf16_f32 v81, v88, v89
	ds_read_b128 v[86:89], v90 offset:63488
	v_add_f32_e32 v197, v105, v94
	ds_read_b128 v[94:97], v111 offset:61440
	ds_read_b128 v[90:93], v90 offset:64512
	s_waitcnt lgkmcnt(4)
	v_mfma_f32_16x16x32_bf16 v[74:77], v[74:77], v[78:81], 0
	v_exp_f32_e32 v198, v100
	v_sub_f32_e32 v112, v112, v214
	v_exp_f32_e32 v112, v112
	s_waitcnt lgkmcnt(3)
	v_mfma_f32_16x16x32_bf16 v[82:85], v[82:85], v[78:81], 0
	v_sub_f32_e32 v110, v110, v214
	v_exp_f32_e32 v110, v110
	v_sub_f32_e32 v113, v113, v214
	s_waitcnt lgkmcnt(2)
	v_mfma_f32_16x16x32_bf16 v[86:89], v[86:89], v[78:81], 0
	v_exp_f32_e32 v113, v113
	s_waitcnt lgkmcnt(0)
	v_mfma_f32_16x16x32_bf16 v[78:81], v[90:93], v[78:81], 0
	v_cvt_pk_bf16_f32 v90, v98, v99
	ds_read_b128 v[98:101], v111 offset:62464
	v_cvt_pk_bf16_f32 v91, v129, v131
	v_cvt_pk_bf16_f32 v92, v135, v137
	v_cvt_pk_bf16_f32 v93, v139, v141
	v_add_u32_e32 v129, s45, v181
	s_nop 0
	v_mfma_f32_16x16x32_bf16 v[74:77], v[94:97], v[90:93], v[74:77]
	ds_read_b128 v[94:97], v111 offset:63488
	s_waitcnt lgkmcnt(1)
	v_mfma_f32_16x16x32_bf16 v[82:85], v[98:101], v[90:93], v[82:85]
	ds_read_b128 v[98:101], v111 offset:64512
	s_waitcnt lgkmcnt(1)
	v_mfma_f32_16x16x32_bf16 v[86:89], v[94:97], v[90:93], v[86:89]
	ds_read_b128 v[94:97], v129 offset:61440
	v_add_f32_e32 v111, v198, v197
	v_add_f32_e32 v111, v112, v111
	s_waitcnt lgkmcnt(1)
	v_mfma_f32_16x16x32_bf16 v[78:81], v[98:101], v[90:93], v[78:81]
	ds_read_b128 v[98:101], v129 offset:62464
	v_cvt_pk_bf16_f32 v90, v122, v123
	v_cvt_pk_bf16_f32 v91, v124, v125
	v_cvt_pk_bf16_f32 v92, v155, v157
	v_cvt_pk_bf16_f32 v93, v187, v188
	v_add_u32_e32 v124, s44, v181
	v_sub_f32_e32 v122, v203, v214
	s_waitcnt lgkmcnt(1)
	v_mfma_f32_16x16x32_bf16 v[74:77], v[94:97], v[90:93], v[74:77]
	ds_read_b128 v[94:97], v129 offset:63488
	v_exp_f32_e32 v122, v122
	v_sub_f32_e32 v123, v204, v214
	s_waitcnt lgkmcnt(1)
	v_mfma_f32_16x16x32_bf16 v[82:85], v[98:101], v[90:93], v[82:85]
	ds_read_b128 v[98:101], v129 offset:64512
	v_exp_f32_e32 v123, v123
	v_sub_f32_e32 v125, v205, v214
	s_waitcnt lgkmcnt(1)
	v_mfma_f32_16x16x32_bf16 v[86:89], v[94:97], v[90:93], v[86:89]
	ds_read_b128 v[94:97], v124 offset:61440
	v_add_f32_e32 v111, v110, v111
	v_add_f32_e32 v111, v113, v111
	s_waitcnt lgkmcnt(1)
	v_mfma_f32_16x16x32_bf16 v[78:81], v[98:101], v[90:93], v[78:81]
	ds_read_b128 v[98:101], v124 offset:62464
	v_cvt_pk_bf16_f32 v90, v189, v190
	v_cvt_pk_bf16_f32 v91, v191, v192
	v_cvt_pk_bf16_f32 v92, v114, v115
	v_cvt_pk_bf16_f32 v93, v116, v117
	v_add_u32_e32 v117, s43, v181
	v_exp_f32_e32 v114, v125
	s_waitcnt lgkmcnt(1)
	v_mfma_f32_16x16x32_bf16 v[74:77], v[94:97], v[90:93], v[74:77]
	ds_read_b128 v[94:97], v124 offset:63488
	v_sub_f32_e32 v115, v206, v214
	v_exp_f32_e32 v115, v115
	s_waitcnt lgkmcnt(1)
	v_mfma_f32_16x16x32_bf16 v[82:85], v[98:101], v[90:93], v[82:85]
	ds_read_b128 v[98:101], v124 offset:64512
	v_sub_f32_e32 v116, v133, v214
	v_add_f32_e32 v111, v122, v111
	s_waitcnt lgkmcnt(1)
	v_mfma_f32_16x16x32_bf16 v[86:89], v[94:97], v[90:93], v[86:89]
	ds_read_b128 v[94:97], v117 offset:61440
	v_exp_f32_e32 v116, v116
	v_add_f32_e32 v111, v123, v111
	s_waitcnt lgkmcnt(1)
	v_mfma_f32_16x16x32_bf16 v[78:81], v[98:101], v[90:93], v[78:81]
	ds_read_b128 v[98:101], v117 offset:62464
	v_cvt_pk_bf16_f32 v90, v119, v120
	v_cvt_pk_bf16_f32 v91, v118, v121
	v_cvt_pk_bf16_f32 v92, v106, v107
	v_cvt_pk_bf16_f32 v93, v108, v109
	v_add_u32_e32 v109, s42, v181
	v_add_f32_e32 v111, v114, v111
	s_waitcnt lgkmcnt(1)
	v_mfma_f32_16x16x32_bf16 v[74:77], v[94:97], v[90:93], v[74:77]
	ds_read_b128 v[94:97], v117 offset:63488
	v_sub_f32_e32 v124, v207, v214
	v_add_f32_e32 v111, v115, v111
	s_waitcnt lgkmcnt(1)
	v_mfma_f32_16x16x32_bf16 v[82:85], v[98:101], v[90:93], v[82:85]
	ds_read_b128 v[98:101], v117 offset:64512
	v_exp_f32_e32 v106, v124
	v_sub_f32_e32 v107, v208, v214
	s_waitcnt lgkmcnt(1)
	v_mfma_f32_16x16x32_bf16 v[86:89], v[94:97], v[90:93], v[86:89]
	ds_read_b128 v[94:97], v109 offset:61440
	v_exp_f32_e32 v107, v107
	v_add_f32_e32 v108, v116, v111
	s_waitcnt lgkmcnt(1)
	v_mfma_f32_16x16x32_bf16 v[78:81], v[98:101], v[90:93], v[78:81]
	ds_read_b128 v[98:101], v109 offset:62464
	v_cvt_pk_bf16_f32 v90, v193, v194
	v_cvt_pk_bf16_f32 v91, v195, v196
	v_cvt_pk_bf16_f32 v92, v102, v103
	v_cvt_pk_bf16_f32 v93, v104, v105
	v_add_u32_e32 v105, s41, v181
	v_sub_f32_e32 v111, v209, v214
	s_waitcnt lgkmcnt(1)
	v_mfma_f32_16x16x32_bf16 v[74:77], v[94:97], v[90:93], v[74:77]
	ds_read_b128 v[94:97], v109 offset:63488
	v_exp_f32_e32 v111, v111
	v_add_f32_e32 v108, v106, v108
	s_waitcnt lgkmcnt(1)
	v_mfma_f32_16x16x32_bf16 v[82:85], v[98:101], v[90:93], v[82:85]
	ds_read_b128 v[98:101], v109 offset:64512
	v_sub_f32_e32 v102, v210, v214
	v_add_f32_e32 v108, v107, v108
	s_waitcnt lgkmcnt(1)
	v_mfma_f32_16x16x32_bf16 v[86:89], v[94:97], v[90:93], v[86:89]
	ds_read_b128 v[94:97], v105 offset:61440
	v_exp_f32_e32 v102, v102
	v_sub_f32_e32 v104, v211, v214
	s_waitcnt lgkmcnt(1)
	v_mfma_f32_16x16x32_bf16 v[78:81], v[98:101], v[90:93], v[78:81]
	ds_read_b128 v[98:101], v105 offset:62464
	v_add_f32_e32 v103, v111, v108
	v_exp_f32_e32 v104, v104
	v_sub_f32_e32 v108, v212, v214
	v_cvt_pk_bf16_f32 v90, v198, v112
	v_cvt_pk_bf16_f32 v91, v110, v113
	v_cvt_pk_bf16_f32 v92, v122, v123
	v_cvt_pk_bf16_f32 v93, v114, v115
	v_exp_f32_e32 v108, v108
	v_sub_f32_e32 v109, v213, v214
	s_waitcnt lgkmcnt(1)
	v_mfma_f32_16x16x32_bf16 v[74:77], v[94:97], v[90:93], v[74:77]
	ds_read_b128 v[94:97], v105 offset:63488
	v_exp_f32_e32 v109, v109
	v_add_f32_e32 v103, v102, v103
	s_waitcnt lgkmcnt(1)
	v_mfma_f32_16x16x32_bf16 v[82:85], v[98:101], v[90:93], v[82:85]
	ds_read_b128 v[98:101], v105 offset:64512
	v_add_f32_e32 v103, v104, v103
	v_add_f32_e32 v103, v108, v103
	v_add_f32_e32 v103, v109, v103
	ds_bpermute_b32 v105, v179, v103
	s_waitcnt lgkmcnt(1)
	v_mfma_f32_16x16x32_bf16 v[78:81], v[98:101], v[90:93], v[78:81]
	v_cvt_pk_bf16_f32 v100, v102, v104
	v_lshlrev_b32_e32 v102, 2, v144
	v_lshl_or_b32 v120, s37, 8, v102
	s_waitcnt lgkmcnt(0)
	v_add_f32_e32 v112, v103, v105
	global_load_dwordx4 v[102:105], v120, s[72:73]
	global_load_dwordx4 v[240:243], v120, s[72:73] offset:64
	global_load_dwordx4 v[244:247], v120, s[72:73] offset:128
	global_load_dwordx4 v[248:251], v120, s[72:73] offset:192
	v_add_u32_e32 v110, s40, v181
	v_mfma_f32_16x16x32_bf16 v[86:89], v[94:97], v[90:93], v[86:89]
	ds_read_b128 v[94:97], v110 offset:61440
	ds_read_b128 v[90:93], v110 offset:62464
	v_cvt_pk_bf16_f32 v98, v116, v106
	v_cvt_pk_bf16_f32 v99, v107, v111
	v_cvt_pk_bf16_f32 v101, v108, v109
	ds_bpermute_b32 v106, v180, v112
	v_and_b32_e32 v113, 0xffff0000, v163
	s_waitcnt lgkmcnt(2)
	v_mfma_f32_16x16x32_bf16 v[94:97], v[94:97], v[98:101], v[74:77]
	v_mov_b32_e32 v157, v127
	s_nop 1
	ds_read_b128 v[74:77], v110 offset:63488
	s_waitcnt lgkmcnt(2)
	v_mfma_f32_16x16x32_bf16 v[82:85], v[90:93], v[98:101], v[82:85]
	ds_read_b128 v[90:93], v110 offset:64512
	s_waitcnt lgkmcnt(1)
	v_mfma_f32_16x16x32_bf16 v[86:89], v[74:77], v[98:101], v[86:89]
	v_add_f32_e32 v74, v112, v106
	v_rcp_f32_e32 v106, v74
	v_lshlrev_b32_e32 v112, 16, v163
	s_waitcnt lgkmcnt(0)
	v_mfma_f32_16x16x32_bf16 v[76:79], v[90:93], v[98:101], v[78:81]
	v_lshlrev_b32_e32 v100, 16, v162
	v_pk_mul_f32 v[96:97], v[96:97], v[106:107] op_sel_hi:[1,0]
	v_pk_mul_f32 v[94:95], v[94:95], v[106:107] op_sel_hi:[1,0]
	v_and_b32_e32 v101, 0xffff0000, v162
	v_mul_f32_e32 v108, 0xbfb8aa3b, v101
	s_nop 2
	v_pk_mul_f32 v[76:77], v[76:77], v[106:107] op_sel_hi:[1,0]
	v_pk_mul_f32 v[74:75], v[78:79], v[106:107] op_sel_hi:[1,0]
	v_mul_f32_e32 v107, 0xbfb8aa3b, v100
	v_exp_f32_e32 v107, v107
	v_exp_f32_e32 v111, v108
	v_pk_mul_f32 v[108:109], v[94:95], v[94:95]
	v_pk_mul_f32 v[98:99], v[96:97], v[96:97]
	v_add_f32_e32 v107, 1.0, v107
	v_rcp_f32_e32 v110, v107
	v_add_f32_e32 v107, 1.0, v111
	v_add_f32_e32 v108, v108, v109
	v_pk_mul_f32 v[82:83], v[82:83], v[106:107] op_sel_hi:[1,0]
	v_add_f32_e32 v98, v98, v108
	v_pk_mul_f32 v[116:117], v[82:83], v[82:83]
	v_add_f32_e32 v98, v99, v98
	v_pk_mul_f32 v[84:85], v[84:85], v[106:107] op_sel_hi:[1,0]
	v_add_f32_e32 v98, v116, v98
	v_pk_mul_f32 v[114:115], v[84:85], v[84:85]
	v_add_f32_e32 v98, v117, v98
	v_pk_mul_f32 v[86:87], v[86:87], v[106:107] op_sel_hi:[1,0]
	v_add_f32_e32 v98, v114, v98
	v_rcp_f32_e32 v111, v107
	v_pk_mul_f32 v[88:89], v[88:89], v[106:107] op_sel_hi:[1,0]
	v_pk_mul_f32 v[106:107], v[86:87], v[86:87]
	v_add_f32_e32 v98, v115, v98
	v_add_f32_e32 v98, v106, v98
	v_pk_mul_f32 v[118:119], v[88:89], v[88:89]
	v_add_f32_e32 v98, v107, v98
	v_add_f32_e32 v98, v118, v98
	v_pk_mul_f32 v[80:81], v[76:77], v[76:77]
	v_add_f32_e32 v98, v119, v98
	v_add_f32_e32 v80, v80, v98
	v_pk_mul_f32 v[78:79], v[74:75], v[74:75]
	v_add_f32_e32 v80, v81, v80
	v_add_f32_e32 v78, v78, v80
	v_add_f32_e32 v78, v79, v78
	ds_bpermute_b32 v79, v179, v78
	v_mul_f32_e32 v80, 0xbfb8aa3b, v112
	v_exp_f32_e32 v80, v80
	v_mul_f32_e32 v81, 0xbfb8aa3b, v113
	v_exp_f32_e32 v81, v81
	s_waitcnt lgkmcnt(0)
	v_add_f32_e32 v98, v78, v79
	ds_bpermute_b32 v99, v180, v98
	v_add_f32_e32 v78, 1.0, v80
	v_add_f32_e32 v79, 1.0, v81
	v_lshl_add_u64 v[90:91], s[0:1], 0, v[156:157]
	v_lshlrev_b32_e32 v92, 1, v144
	s_waitcnt lgkmcnt(0)
	v_add_f32_e32 v80, v98, v99
	v_fmamk_f32 v80, v80, 0x3c800000, v185
	v_mul_f32_e32 v81, 0x4b800000, v80
	v_cmp_gt_f32_e32 vcc, s34, v80
	v_mov_b32_e32 v93, v127
	v_lshl_add_u64 v[90:91], v[90:91], 0, v[92:93]
	v_cndmask_b32_e32 v80, v80, v81, vcc
	v_rsq_f32_e32 v98, v80
	v_rcp_f32_e32 v78, v78
	v_rcp_f32_e32 v79, v79
	v_pk_mul_f32 v[80:81], v[110:111], v[100:101]
	v_mul_f32_e32 v92, 0x45800000, v98
	v_cndmask_b32_e32 v92, v98, v92, vcc
	v_pk_mul_f32 v[94:95], v[94:95], v[92:93] op_sel_hi:[1,0]
	v_pk_mul_f32 v[78:79], v[78:79], v[112:113]
	s_waitcnt vmcnt(0)
	v_pk_mul_f32 v[94:95], v[102:103], v[94:95]
	v_lshlrev_b32_e32 v98, 16, v161
	v_pk_mul_f32 v[80:81], v[80:81], v[94:95]
	v_pk_mul_f32 v[94:95], v[96:97], v[92:93] op_sel_hi:[1,0]
	v_cvt_pk_bf16_f32 v80, v80, v81
	v_pk_mul_f32 v[94:95], v[104:105], v[94:95]
	v_and_b32_e32 v99, 0xffff0000, v161
	v_pk_mul_f32 v[78:79], v[78:79], v[94:95]
	v_lshlrev_b32_e32 v94, 16, v160
	v_cvt_pk_bf16_f32 v81, v78, v79
	global_store_dwordx2 v[90:91], v[80:81], off nt
	v_and_b32_e32 v95, 0xffff0000, v160
	v_mul_f32_e32 v93, 0xbfb8aa3b, v94
	v_exp_f32_e32 v93, v93
	v_mul_f32_e32 v96, 0xbfb8aa3b, v95
	v_exp_f32_e32 v97, v96
	s_and_b64 vcc, exec, s[28:29]
	v_add_f32_e32 v93, 1.0, v93
	v_rcp_f32_e32 v96, v93
	v_add_f32_e32 v93, 1.0, v97
	v_mul_f32_e32 v97, 0xbfb8aa3b, v98
	v_exp_f32_e32 v100, v97
	v_mul_f32_e32 v97, 0xbfb8aa3b, v99
	v_exp_f32_e32 v101, v97
	v_rcp_f32_e32 v97, v93
	v_add_f32_e32 v93, 1.0, v100
	v_rcp_f32_e32 v100, v93
	v_add_f32_e32 v93, 1.0, v101
	v_rcp_f32_e32 v101, v93
	v_pk_mul_f32 v[82:83], v[82:83], v[92:93] op_sel_hi:[1,0]
	v_pk_mul_f32 v[94:95], v[96:97], v[94:95]
	v_pk_mul_f32 v[76:77], v[76:77], v[92:93] op_sel_hi:[1,0]
	v_pk_mul_f32 v[96:97], v[100:101], v[98:99]
	v_pk_mul_f32 v[74:75], v[74:75], v[92:93] op_sel_hi:[1,0]
	v_mov_b64_e32 v[160:161], v[166:167]
	v_mov_b64_e32 v[162:163], v[164:165]
	v_pk_mul_f32 v[78:79], v[240:241], v[82:83]
	v_pk_mul_f32 v[82:83], v[84:85], v[92:93] op_sel_hi:[1,0]
	v_pk_mul_f32 v[78:79], v[94:95], v[78:79]
	v_pk_mul_f32 v[80:81], v[242:243], v[82:83]
	v_cvt_pk_bf16_f32 v78, v78, v79
	v_pk_mul_f32 v[80:81], v[96:97], v[80:81]
	v_lshlrev_b32_e32 v82, 16, v158
	v_cvt_pk_bf16_f32 v79, v80, v81
	global_store_dwordx2 v[90:91], v[78:79], off offset:32 nt
	v_and_b32_e32 v83, 0xffff0000, v158
	v_mul_f32_e32 v84, 0xbfb8aa3b, v82
	v_mul_f32_e32 v85, 0xbfb8aa3b, v83
	v_exp_f32_e32 v84, v84
	v_exp_f32_e32 v85, v85
	v_add_f32_e32 v84, 1.0, v84
	v_add_f32_e32 v85, 1.0, v85
	v_rcp_f32_e32 v84, v84
	v_rcp_f32_e32 v85, v85
	s_nop 0
	v_pk_mul_f32 v[82:83], v[84:85], v[82:83]
	v_pk_mul_f32 v[84:85], v[86:87], v[92:93] op_sel_hi:[1,0]
	v_pk_mul_f32 v[78:79], v[244:245], v[84:85]
	v_lshlrev_b32_e32 v84, 16, v159
	v_and_b32_e32 v85, 0xffff0000, v159
	v_mul_f32_e32 v86, 0xbfb8aa3b, v84
	v_mul_f32_e32 v87, 0xbfb8aa3b, v85
	v_exp_f32_e32 v86, v86
	v_exp_f32_e32 v87, v87
	v_pk_mul_f32 v[78:79], v[82:83], v[78:79]
	v_mov_b64_e32 v[158:159], v[168:169]
	v_add_f32_e32 v82, 1.0, v86
	v_add_f32_e32 v83, 1.0, v87
	v_rcp_f32_e32 v82, v82
	v_rcp_f32_e32 v83, v83
	v_pk_mul_f32 v[86:87], v[88:89], v[92:93] op_sel_hi:[1,0]
	v_cvt_pk_bf16_f32 v78, v78, v79
	v_pk_mul_f32 v[80:81], v[246:247], v[86:87]
	v_pk_mul_f32 v[82:83], v[82:83], v[84:85]
	s_nop 0
	v_pk_mul_f32 v[80:81], v[82:83], v[80:81]
	v_lshlrev_b32_e32 v82, 16, v146
	v_cvt_pk_bf16_f32 v79, v80, v81
	global_store_dwordx2 v[90:91], v[78:79], off offset:64 nt
	v_and_b32_e32 v83, 0xffff0000, v146
	v_mul_f32_e32 v84, 0xbfb8aa3b, v82
	v_mul_f32_e32 v85, 0xbfb8aa3b, v83
	v_exp_f32_e32 v84, v84
	v_exp_f32_e32 v85, v85
	v_add_f32_e32 v84, 1.0, v84
	v_add_f32_e32 v85, 1.0, v85
	v_rcp_f32_e32 v84, v84
	v_rcp_f32_e32 v85, v85
	v_pk_mul_f32 v[76:77], v[248:249], v[76:77]
	v_pk_mul_f32 v[78:79], v[84:85], v[82:83]
	v_lshlrev_b32_e32 v82, 16, v147
	v_and_b32_e32 v83, 0xffff0000, v147
	v_mul_f32_e32 v84, 0xbfb8aa3b, v82
	v_mul_f32_e32 v85, 0xbfb8aa3b, v83
	v_exp_f32_e32 v84, v84
	v_exp_f32_e32 v85, v85
	v_pk_mul_f32 v[76:77], v[78:79], v[76:77]
	v_pk_mul_f32 v[74:75], v[250:251], v[74:75]
	v_add_f32_e32 v78, 1.0, v84
	v_add_f32_e32 v79, 1.0, v85
	v_rcp_f32_e32 v78, v78
	v_rcp_f32_e32 v79, v79
	v_cvt_pk_bf16_f32 v76, v76, v77
	v_mov_b64_e32 v[146:147], v[170:171]
	v_pk_mul_f32 v[78:79], v[78:79], v[82:83]
	s_nop 0
	v_pk_mul_f32 v[74:75], v[78:79], v[74:75]
	v_mov_b64_e32 v[80:81], v[68:69]
	v_cvt_pk_bf16_f32 v77, v74, v75
	global_store_dwordx2 v[90:91], v[76:77], off offset:96 nt
	v_mov_b64_e32 v[76:77], v[72:73]
	v_mov_b64_e32 v[74:75], v[70:71]
	v_mov_b64_e32 v[78:79], v[66:67]
	s_cbranch_vccnz .LBB0_461
